# grid-barrier spin loops: s_sleep 6 instead of s_sleep 1 between polls (less polling traffic and idle power during tails)
# speedup vs baseline: 1.0051x; 1.0051x over previous
; __global__ void __launch_bounds__(NTHREADS, 2) fwd_megakernel(Args a) {
;     ...
;     if (a.ws == nullptr) grid.sync();
.LBB0_55:
	s_sleep 6
	global_load_dword v2, v0, s[4:5] offset:32 sc1
	s_waitcnt vmcnt(0)
	v_and_b32_e32 v2, 0xffff0000, v2
	v_cmp_ne_u32_e32 vcc, v2, v1
	s_or_b64 s[6:7], vcc, s[6:7]
	s_andn2_b64 exec, exec, s[6:7]
	s_cbranch_execnz .LBB0_55

; DI unsigned xb_ld(unsigned* p)              { return __hip_atomic_load(p, __ATOMIC_RELAXED, __HIP_MEMORY_SCOPE_AGENT); }
; DI void xcd_barrier_complete(unsigned* bar, unsigned x, unsigned& nloc, unsigned& nx) {
;     const unsigned G = gridDim.x * gridDim.y * gridDim.z;
;     unsigned sum, cnt, mine, sp = 0u;
;     for (;;) {
;         sum = 0u; cnt = 0u; mine = 0u;
; #pragma unroll
;         for (unsigned j = 0; j < 16; ++j) { const unsigned c = xb_ld(&bar[XB_XCNT(j)]); sum += c; cnt += (c > 0u) ? 1u : 0u; mine = (j == x) ? c : mine; }
;         if (sum == G) break;
;         __builtin_amdgcn_s_sleep(1);
;         if ((++sp & 255u) == 0u) { if (xb_ld(&bar[XB_TMO])) break; if (sp > XB_SPIN_CAP) { atomicAdd(&bar[XB_TMO], 1u); break; } }
;     }
;     nloc = mine > 0u ? mine : 1u; nx = cnt > 0u ? cnt : 1u;
; }
.LBB0_62:
	global_load_dword v15, v16, s[6:7] sc1
	s_waitcnt lgkmcnt(0)
	global_load_dword v0, v16, s[8:9] sc1
	global_load_dword v1, v16, s[10:11] sc1
	global_load_dword v2, v16, s[12:13] sc1
	global_load_dword v3, v16, s[14:15] sc1
	global_load_dword v4, v16, s[16:17] sc1
	global_load_dword v5, v16, s[18:19] sc1
	global_load_dword v6, v16, s[20:21] sc1
	global_load_dword v7, v16, s[22:23] sc1
	global_load_dword v8, v16, s[34:35] sc1
	global_load_dword v9, v16, s[36:37] sc1
	global_load_dword v10, v16, s[38:39] sc1
	global_load_dword v11, v16, s[40:41] sc1
	global_load_dword v12, v16, s[42:43] sc1
	global_load_dword v13, v16, s[44:45] sc1
	global_load_dword v14, v16, s[46:47] sc1
	s_mov_b64 s[48:49], -1
	s_mov_b64 s[50:51], -1
	s_waitcnt vmcnt(14)
	v_add_u32_e32 v17, v0, v15
	s_waitcnt vmcnt(13)
	v_add_u32_e32 v17, v17, v1
	s_waitcnt vmcnt(12)
	v_add_u32_e32 v17, v17, v2
	s_waitcnt vmcnt(11)
	v_add_u32_e32 v17, v17, v3
	s_waitcnt vmcnt(10)
	v_add_u32_e32 v17, v17, v4
	s_waitcnt vmcnt(9)
	v_add_u32_e32 v17, v17, v5
	s_waitcnt vmcnt(8)
	v_add_u32_e32 v17, v17, v6
	s_waitcnt vmcnt(7)
	v_add_u32_e32 v17, v17, v7
	s_waitcnt vmcnt(6)
	v_add_u32_e32 v17, v17, v8
	s_waitcnt vmcnt(5)
	v_add_u32_e32 v17, v17, v9
	s_waitcnt vmcnt(4)
	v_add_u32_e32 v17, v17, v10
	s_waitcnt vmcnt(3)
	v_add_u32_e32 v17, v17, v11
	s_waitcnt vmcnt(2)
	v_add_u32_e32 v17, v17, v12
	s_waitcnt vmcnt(1)
	v_add_u32_e32 v17, v17, v13
	s_waitcnt vmcnt(0)
	v_add_u32_e32 v17, v17, v14
	v_cmp_eq_u32_e32 vcc, s3, v17
	s_cbranch_vccnz .LBB0_61
	s_and_b32 s48, s33, 0xff
	s_cmp_eq_u32 s48, 0
	s_mov_b64 s[48:49], -1
	s_mov_b64 s[52:53], -1
	s_sleep 6
	s_cbranch_scc0 .LBB0_66
	global_load_dword v17, v16, s[4:5] sc1
	s_waitcnt vmcnt(0)
	v_cmp_eq_u32_e32 vcc, 0, v17
	s_cbranch_vccnz .LBB0_68
	s_mov_b64 s[52:53], 0

; DI unsigned xb_ld(unsigned* p)              { return __hip_atomic_load(p, __ATOMIC_RELAXED, __HIP_MEMORY_SCOPE_AGENT); }
; DI unsigned xb_add(unsigned* p, unsigned v) { return __hip_atomic_fetch_add(p, v, __ATOMIC_RELAXED, __HIP_MEMORY_SCOPE_AGENT); }
; #define XB_SPIN(cond, bar) do { unsigned _sp = 0; while (cond) { __builtin_amdgcn_s_sleep(1); \
;     if ((++_sp & 255u) == 0u) { if (xb_ld(&(bar)[XB_TMO])) break; if (_sp > XB_SPIN_CAP) { atomicAdd(&(bar)[XB_TMO], 1u); break; } } } } while (0)
; DI void xcd_barrier(const XcdBarrier& b) {
;     ...
;             else XB_SPIN(xb_ld(&bar[XB_TOPGEN]) == tg, bar);
;             __builtin_amdgcn_fence(__ATOMIC_ACQUIRE, "agent");
;             xb_add(&bar[XB_XGEN(b.x)], 1u);
;             asm volatile("s_waitcnt vmcnt(0)" ::: "memory");
;         } else {
;             XB_SPIN(xb_ld(&bar[XB_XGEN(b.x)]) == gen, bar);
.LBB0_80:
	s_and_b32 s3, s2, 0xff
	s_mov_b64 s[18:19], -1
	s_cmp_lg_u32 s3, 0
	s_mov_b64 s[22:23], -1
	s_sleep 6
	s_cbranch_scc1 .LBB0_83
	global_load_dword v2, v0, s[10:11] sc1
	s_waitcnt vmcnt(0)
	v_cmp_eq_u32_e32 vcc, 0, v2
	s_cbranch_vccnz .LBB0_85
	s_mov_b64 s[22:23], 0
	s_mov_b64 s[20:21], -1

; DI unsigned xb_ld(unsigned* p)              { return __hip_atomic_load(p, __ATOMIC_RELAXED, __HIP_MEMORY_SCOPE_AGENT); }
; DI unsigned xb_add(unsigned* p, unsigned v) { return __hip_atomic_fetch_add(p, v, __ATOMIC_RELAXED, __HIP_MEMORY_SCOPE_AGENT); }
; #define XB_SPIN(cond, bar) do { unsigned _sp = 0; while (cond) { __builtin_amdgcn_s_sleep(1); \
;     if ((++_sp & 255u) == 0u) { if (xb_ld(&(bar)[XB_TMO])) break; if (_sp > XB_SPIN_CAP) { atomicAdd(&(bar)[XB_TMO], 1u); break; } } } } while (0)
; DI void xcd_barrier(const XcdBarrier& b) {
;     ...
;             else XB_SPIN(xb_ld(&bar[XB_TOPGEN]) == tg, bar);
;             __builtin_amdgcn_fence(__ATOMIC_ACQUIRE, "agent");
;             xb_add(&bar[XB_XGEN(b.x)], 1u);
;             asm volatile("s_waitcnt vmcnt(0)" ::: "memory");
;         } else {
;             XB_SPIN(xb_ld(&bar[XB_XGEN(b.x)]) == gen, bar);
.LBB0_97:
	s_and_b32 s3, s2, 0xff
	s_cmp_lg_u32 s3, 0
	s_mov_b64 s[20:21], -1
	s_sleep 6
	s_cbranch_scc1 .LBB0_100
	global_load_dword v1, v0, s[10:11] sc1
	s_waitcnt vmcnt(0)
	v_cmp_eq_u32_e32 vcc, 0, v1
	s_cbranch_vccnz .LBB0_102
	s_mov_b64 s[20:21], 0
	s_mov_b64 s[18:19], -1

; DI unsigned xb_ld(unsigned* p)              { return __hip_atomic_load(p, __ATOMIC_RELAXED, __HIP_MEMORY_SCOPE_AGENT); }
; DI void xcd_barrier_complete(unsigned* bar, unsigned x, unsigned& nloc, unsigned& nx) {
;     const unsigned G = gridDim.x * gridDim.y * gridDim.z;
;     unsigned sum, cnt, mine, sp = 0u;
;     for (;;) {
;         sum = 0u; cnt = 0u; mine = 0u;
; #pragma unroll
;         for (unsigned j = 0; j < 16; ++j) { const unsigned c = xb_ld(&bar[XB_XCNT(j)]); sum += c; cnt += (c > 0u) ? 1u : 0u; mine = (j == x) ? c : mine; }
;         if (sum == G) break;
;         __builtin_amdgcn_s_sleep(1);
;         if ((++sp & 255u) == 0u) { if (xb_ld(&bar[XB_TMO])) break; if (sp > XB_SPIN_CAP) { atomicAdd(&bar[XB_TMO], 1u); break; } }
;     }
;     nloc = mine > 0u ? mine : 1u; nx = cnt > 0u ? cnt : 1u;
; }
.LBB0_197:
	v_readlane_b32 s4, v253, 54
	v_readlane_b32 s5, v253, 55
	s_waitcnt lgkmcnt(0)
	global_load_dword v0, v181, s[66:67] sc1
	s_mov_b64 s[6:7], -1
	s_nop 1
	global_load_dword v1, v181, s[4:5] sc1
	v_readlane_b32 s4, v253, 56
	v_readlane_b32 s5, v253, 57
	s_waitcnt vmcnt(0)
	v_add_u32_e32 v16, v1, v0
	s_nop 2
	global_load_dword v2, v181, s[4:5] sc1
	v_readlane_b32 s4, v253, 58
	v_readlane_b32 s5, v253, 59
	s_waitcnt vmcnt(0)
	v_add_u32_e32 v16, v16, v2
	s_nop 2
	global_load_dword v3, v181, s[4:5] sc1
	v_readlane_b32 s4, v253, 60
	v_readlane_b32 s5, v253, 61
	s_waitcnt vmcnt(0)
	v_add_u32_e32 v16, v16, v3
	s_nop 2
	global_load_dword v4, v181, s[4:5] sc1
	v_readlane_b32 s4, v253, 62
	v_readlane_b32 s5, v253, 63
	s_waitcnt vmcnt(0)
	v_add_u32_e32 v16, v16, v4
	s_nop 2
	global_load_dword v5, v181, s[4:5] sc1
	v_readlane_b32 s4, v254, 0
	v_readlane_b32 s5, v254, 1
	s_waitcnt vmcnt(0)
	v_add_u32_e32 v16, v16, v5
	s_nop 2
	global_load_dword v6, v181, s[4:5] sc1
	v_readlane_b32 s4, v254, 2
	v_readlane_b32 s5, v254, 3
	s_nop 4
	global_load_dword v7, v181, s[4:5] sc1
	global_load_dword v8, v181, s[22:23] sc1
	global_load_dword v9, v181, s[2:3] sc1
	global_load_dword v10, v181, s[34:35] sc1
	global_load_dword v11, v181, s[86:87] sc1
	global_load_dword v12, v181, s[36:37] sc1
	global_load_dword v13, v181, s[40:41] sc1
	global_load_dword v14, v181, s[48:49] sc1
	global_load_dword v15, v181, s[50:51] sc1
	s_mov_b64 s[4:5], -1
	s_waitcnt vmcnt(9)
	v_add_u32_e32 v16, v16, v6
	s_waitcnt vmcnt(8)
	v_add_u32_e32 v16, v16, v7
	s_waitcnt vmcnt(7)
	v_add_u32_e32 v16, v16, v8
	s_waitcnt vmcnt(6)
	v_add_u32_e32 v16, v16, v9
	s_waitcnt vmcnt(5)
	v_add_u32_e32 v16, v16, v10
	s_waitcnt vmcnt(4)
	v_add_u32_e32 v16, v16, v11
	s_waitcnt vmcnt(3)
	v_add_u32_e32 v16, v16, v12
	s_waitcnt vmcnt(2)
	v_add_u32_e32 v16, v16, v13
	s_waitcnt vmcnt(1)
	v_add_u32_e32 v16, v16, v14
	s_waitcnt vmcnt(0)
	v_add_u32_e32 v16, v16, v15
	v_cmp_eq_u32_e32 vcc, s16, v16
	s_cbranch_vccnz .LBB0_196
	s_and_b32 s4, s11, 0xff
	s_cmp_eq_u32 s4, 0
	s_mov_b64 s[4:5], -1
	s_mov_b64 s[8:9], -1
	s_sleep 6
	s_cbranch_scc0 .LBB0_201
	global_load_dword v16, v181, s[64:65] sc1
	s_waitcnt vmcnt(0)
	v_cmp_eq_u32_e32 vcc, 0, v16
	s_cbranch_vccnz .LBB0_203
	s_mov_b64 s[8:9], 0

; DI unsigned xb_ld(unsigned* p)              { return __hip_atomic_load(p, __ATOMIC_RELAXED, __HIP_MEMORY_SCOPE_AGENT); }
; DI unsigned xb_add(unsigned* p, unsigned v) { return __hip_atomic_fetch_add(p, v, __ATOMIC_RELAXED, __HIP_MEMORY_SCOPE_AGENT); }
; #define XB_SPIN(cond, bar) do { unsigned _sp = 0; while (cond) { __builtin_amdgcn_s_sleep(1); \
;     if ((++_sp & 255u) == 0u) { if (xb_ld(&(bar)[XB_TMO])) break; if (_sp > XB_SPIN_CAP) { atomicAdd(&(bar)[XB_TMO], 1u); break; } } } } while (0)
; DI void xcd_barrier(const XcdBarrier& b) {
;     ...
;             else XB_SPIN(xb_ld(&bar[XB_TOPGEN]) == tg, bar);
;             __builtin_amdgcn_fence(__ATOMIC_ACQUIRE, "agent");
;             xb_add(&bar[XB_XGEN(b.x)], 1u);
;             asm volatile("s_waitcnt vmcnt(0)" ::: "memory");
;         } else {
;             XB_SPIN(xb_ld(&bar[XB_XGEN(b.x)]) == gen, bar);
.LBB0_215:
	s_and_b32 s18, s46, 0xff
	s_mov_b64 s[16:17], -1
	s_cmp_lg_u32 s18, 0
	s_mov_b64 s[20:21], -1
	s_sleep 6
	s_cbranch_scc1 .LBB0_218
	global_load_dword v0, v181, s[64:65] sc1
	s_waitcnt vmcnt(0)
	v_cmp_eq_u32_e32 vcc, 0, v0
	s_cbranch_vccnz .LBB0_220
	s_mov_b64 s[20:21], 0
	s_mov_b64 s[18:19], -1

; DI unsigned xb_ld(unsigned* p)              { return __hip_atomic_load(p, __ATOMIC_RELAXED, __HIP_MEMORY_SCOPE_AGENT); }
; DI unsigned xb_add(unsigned* p, unsigned v) { return __hip_atomic_fetch_add(p, v, __ATOMIC_RELAXED, __HIP_MEMORY_SCOPE_AGENT); }
; #define XB_SPIN(cond, bar) do { unsigned _sp = 0; while (cond) { __builtin_amdgcn_s_sleep(1); \
;     if ((++_sp & 255u) == 0u) { if (xb_ld(&(bar)[XB_TMO])) break; if (_sp > XB_SPIN_CAP) { atomicAdd(&(bar)[XB_TMO], 1u); break; } } } } while (0)
; DI void xcd_barrier(const XcdBarrier& b) {
;     ...
;             else XB_SPIN(xb_ld(&bar[XB_TOPGEN]) == tg, bar);
;             __builtin_amdgcn_fence(__ATOMIC_ACQUIRE, "agent");
;             xb_add(&bar[XB_XGEN(b.x)], 1u);
;             asm volatile("s_waitcnt vmcnt(0)" ::: "memory");
;         } else {
;             XB_SPIN(xb_ld(&bar[XB_XGEN(b.x)]) == gen, bar);
.LBB0_232:
	s_and_b32 s16, s20, 0xff
	s_mov_b64 s[14:15], -1
	s_cmp_lg_u32 s16, 0
	s_mov_b64 s[18:19], -1
	s_sleep 6
	s_cbranch_scc1 .LBB0_235
	global_load_dword v0, v181, s[64:65] sc1
	s_waitcnt vmcnt(0)
	v_cmp_eq_u32_e32 vcc, 0, v0
	s_cbranch_vccnz .LBB0_237
	s_mov_b64 s[18:19], 0
	s_mov_b64 s[16:17], -1

; DI unsigned xb_ld(unsigned* p)              { return __hip_atomic_load(p, __ATOMIC_RELAXED, __HIP_MEMORY_SCOPE_AGENT); }
; DI void xcd_barrier_complete(unsigned* bar, unsigned x, unsigned& nloc, unsigned& nx) {
;     const unsigned G = gridDim.x * gridDim.y * gridDim.z;
;     unsigned sum, cnt, mine, sp = 0u;
;     for (;;) {
;         sum = 0u; cnt = 0u; mine = 0u;
; #pragma unroll
;         for (unsigned j = 0; j < 16; ++j) { const unsigned c = xb_ld(&bar[XB_XCNT(j)]); sum += c; cnt += (c > 0u) ? 1u : 0u; mine = (j == x) ? c : mine; }
;         if (sum == G) break;
;         __builtin_amdgcn_s_sleep(1);
;         if ((++sp & 255u) == 0u) { if (xb_ld(&bar[XB_TMO])) break; if (sp > XB_SPIN_CAP) { atomicAdd(&bar[XB_TMO], 1u); break; } }
;     }
;     nloc = mine > 0u ? mine : 1u; nx = cnt > 0u ? cnt : 1u;
; }
.LBB0_309:
	v_readlane_b32 s46, v253, 54
	v_readlane_b32 s47, v253, 55
	global_load_dword v104, v181, s[66:67] sc1
	s_mov_b64 s[72:73], -1
	s_mov_b64 s[74:75], -1
	s_nop 1
	global_load_dword v105, v181, s[46:47] sc1
	v_readlane_b32 s46, v253, 56
	v_readlane_b32 s47, v253, 57
	s_waitcnt vmcnt(0)
	v_add_u32_e32 v120, v105, v104
	s_nop 2
	global_load_dword v106, v181, s[46:47] sc1
	v_readlane_b32 s46, v253, 58
	v_readlane_b32 s47, v253, 59
	s_waitcnt vmcnt(0)
	v_add_u32_e32 v120, v120, v106
	s_nop 2
	global_load_dword v107, v181, s[46:47] sc1
	v_readlane_b32 s46, v253, 60
	v_readlane_b32 s47, v253, 61
	s_waitcnt vmcnt(0)
	v_add_u32_e32 v120, v120, v107
	s_nop 2
	global_load_dword v108, v181, s[46:47] sc1
	v_readlane_b32 s46, v253, 62
	v_readlane_b32 s47, v253, 63
	s_waitcnt vmcnt(0)
	v_add_u32_e32 v120, v120, v108
	s_nop 2
	global_load_dword v109, v181, s[46:47] sc1
	v_readlane_b32 s46, v254, 0
	v_readlane_b32 s47, v254, 1
	s_waitcnt vmcnt(0)
	v_add_u32_e32 v120, v120, v109
	s_nop 2
	global_load_dword v110, v181, s[46:47] sc1
	v_readlane_b32 s46, v254, 2
	v_readlane_b32 s47, v254, 3
	s_nop 4
	global_load_dword v111, v181, s[46:47] sc1
	global_load_dword v112, v181, s[22:23] sc1
	global_load_dword v113, v181, s[2:3] sc1
	global_load_dword v114, v181, s[34:35] sc1
	global_load_dword v115, v181, s[86:87] sc1
	global_load_dword v116, v181, s[36:37] sc1
	global_load_dword v117, v181, s[40:41] sc1
	global_load_dword v118, v181, s[48:49] sc1
	global_load_dword v119, v181, s[50:51] sc1
	s_waitcnt vmcnt(9)
	v_add_u32_e32 v120, v120, v110
	s_waitcnt vmcnt(8)
	v_add_u32_e32 v120, v120, v111
	s_waitcnt vmcnt(7)
	v_add_u32_e32 v120, v120, v112
	s_waitcnt vmcnt(6)
	v_add_u32_e32 v120, v120, v113
	s_waitcnt vmcnt(5)
	v_add_u32_e32 v120, v120, v114
	s_waitcnt vmcnt(4)
	v_add_u32_e32 v120, v120, v115
	s_waitcnt vmcnt(3)
	v_add_u32_e32 v120, v120, v116
	s_waitcnt vmcnt(2)
	v_add_u32_e32 v120, v120, v117
	s_waitcnt vmcnt(1)
	v_add_u32_e32 v120, v120, v118
	s_waitcnt vmcnt(0)
	v_add_u32_e32 v120, v120, v119
	v_cmp_eq_u32_e32 vcc, s70, v120
	s_cbranch_vccnz .LBB0_308
	s_and_b32 s46, s71, 0xff
	s_cmp_eq_u32 s46, 0
	s_mov_b64 s[46:47], -1
	s_sleep 6
	s_cbranch_scc0 .LBB0_313
	global_load_dword v120, v181, s[64:65] sc1
	s_waitcnt vmcnt(0)
	v_cmp_eq_u32_e32 vcc, 0, v120
	s_cbranch_vccnz .LBB0_315
	s_mov_b64 s[46:47], 0

; DI unsigned xb_ld(unsigned* p)              { return __hip_atomic_load(p, __ATOMIC_RELAXED, __HIP_MEMORY_SCOPE_AGENT); }
; DI unsigned xb_add(unsigned* p, unsigned v) { return __hip_atomic_fetch_add(p, v, __ATOMIC_RELAXED, __HIP_MEMORY_SCOPE_AGENT); }
; #define XB_SPIN(cond, bar) do { unsigned _sp = 0; while (cond) { __builtin_amdgcn_s_sleep(1); \
;     if ((++_sp & 255u) == 0u) { if (xb_ld(&(bar)[XB_TMO])) break; if (_sp > XB_SPIN_CAP) { atomicAdd(&(bar)[XB_TMO], 1u); break; } } } } while (0)
; DI void xcd_barrier(const XcdBarrier& b) {
;     ...
;             else XB_SPIN(xb_ld(&bar[XB_TOPGEN]) == tg, bar);
;             __builtin_amdgcn_fence(__ATOMIC_ACQUIRE, "agent");
;             xb_add(&bar[XB_XGEN(b.x)], 1u);
;             asm volatile("s_waitcnt vmcnt(0)" ::: "memory");
;         } else {
;             XB_SPIN(xb_ld(&bar[XB_XGEN(b.x)]) == gen, bar);
.LBB0_327:
	s_and_b32 s46, s89, 0xff
	s_mov_b64 s[70:71], -1
	s_cmp_lg_u32 s46, 0
	s_mov_b64 vcc, -1
	s_sleep 6
	s_cbranch_scc1 .LBB0_330
	global_load_dword v104, v181, s[64:65] sc1
	s_waitcnt vmcnt(0)
	v_cmp_eq_u32_e32 vcc, 0, v104
	s_cbranch_vccnz .LBB0_332
	s_mov_b64 vcc, 0
	s_mov_b64 s[46:47], -1

; DI unsigned xb_ld(unsigned* p)              { return __hip_atomic_load(p, __ATOMIC_RELAXED, __HIP_MEMORY_SCOPE_AGENT); }
; DI unsigned xb_add(unsigned* p, unsigned v) { return __hip_atomic_fetch_add(p, v, __ATOMIC_RELAXED, __HIP_MEMORY_SCOPE_AGENT); }
; #define XB_SPIN(cond, bar) do { unsigned _sp = 0; while (cond) { __builtin_amdgcn_s_sleep(1); \
;     if ((++_sp & 255u) == 0u) { if (xb_ld(&(bar)[XB_TMO])) break; if (_sp > XB_SPIN_CAP) { atomicAdd(&(bar)[XB_TMO], 1u); break; } } } } while (0)
; DI void xcd_barrier(const XcdBarrier& b) {
;     ...
;             else XB_SPIN(xb_ld(&bar[XB_TOPGEN]) == tg, bar);
;             __builtin_amdgcn_fence(__ATOMIC_ACQUIRE, "agent");
;             xb_add(&bar[XB_XGEN(b.x)], 1u);
;             asm volatile("s_waitcnt vmcnt(0)" ::: "memory");
;         } else {
;             XB_SPIN(xb_ld(&bar[XB_XGEN(b.x)]) == gen, bar);
.LBB0_344:
	s_and_b32 s46, s89, 0xff
	s_mov_b64 s[82:83], -1
	s_cmp_lg_u32 s46, 0
	s_mov_b64 s[70:71], -1
	s_sleep 6
	s_cbranch_scc1 .LBB0_347
	global_load_dword v104, v181, s[64:65] sc1
	s_waitcnt vmcnt(0)
	v_cmp_eq_u32_e32 vcc, 0, v104
	s_cbranch_vccnz .LBB0_349
	s_mov_b64 s[70:71], 0
	s_mov_b64 s[46:47], -1

; DI unsigned xb_ld(unsigned* p)              { return __hip_atomic_load(p, __ATOMIC_RELAXED, __HIP_MEMORY_SCOPE_AGENT); }
; DI void xcd_barrier_complete(unsigned* bar, unsigned x, unsigned& nloc, unsigned& nx) {
;     const unsigned G = gridDim.x * gridDim.y * gridDim.z;
;     unsigned sum, cnt, mine, sp = 0u;
;     for (;;) {
;         sum = 0u; cnt = 0u; mine = 0u;
; #pragma unroll
;         for (unsigned j = 0; j < 16; ++j) { const unsigned c = xb_ld(&bar[XB_XCNT(j)]); sum += c; cnt += (c > 0u) ? 1u : 0u; mine = (j == x) ? c : mine; }
;         if (sum == G) break;
;         __builtin_amdgcn_s_sleep(1);
;         if ((++sp & 255u) == 0u) { if (xb_ld(&bar[XB_TMO])) break; if (sp > XB_SPIN_CAP) { atomicAdd(&bar[XB_TMO], 1u); break; } }
;     }
;     nloc = mine > 0u ? mine : 1u; nx = cnt > 0u ? cnt : 1u;
; }
.LBB0_390:
	v_readlane_b32 s46, v253, 54
	v_readlane_b32 s47, v253, 55
	global_load_dword v104, v181, s[66:67] sc1
	s_mov_b64 s[70:71], -1
	s_mov_b64 s[72:73], -1
	s_nop 1
	global_load_dword v105, v181, s[46:47] sc1
	v_readlane_b32 s46, v253, 56
	v_readlane_b32 s47, v253, 57
	s_waitcnt vmcnt(0)
	v_add_u32_e32 v120, v105, v104
	s_nop 2
	global_load_dword v106, v181, s[46:47] sc1
	v_readlane_b32 s46, v253, 58
	v_readlane_b32 s47, v253, 59
	s_waitcnt vmcnt(0)
	v_add_u32_e32 v120, v120, v106
	s_nop 2
	global_load_dword v107, v181, s[46:47] sc1
	v_readlane_b32 s46, v253, 60
	v_readlane_b32 s47, v253, 61
	s_waitcnt vmcnt(0)
	v_add_u32_e32 v120, v120, v107
	s_nop 2
	global_load_dword v108, v181, s[46:47] sc1
	v_readlane_b32 s46, v253, 62
	v_readlane_b32 s47, v253, 63
	s_waitcnt vmcnt(0)
	v_add_u32_e32 v120, v120, v108
	s_nop 2
	global_load_dword v109, v181, s[46:47] sc1
	v_readlane_b32 s46, v254, 0
	v_readlane_b32 s47, v254, 1
	s_waitcnt vmcnt(0)
	v_add_u32_e32 v120, v120, v109
	s_nop 2
	global_load_dword v110, v181, s[46:47] sc1
	v_readlane_b32 s46, v254, 2
	v_readlane_b32 s47, v254, 3
	s_nop 4
	global_load_dword v111, v181, s[46:47] sc1
	global_load_dword v112, v181, s[22:23] sc1
	global_load_dword v113, v181, s[2:3] sc1
	global_load_dword v114, v181, s[34:35] sc1
	global_load_dword v115, v181, s[86:87] sc1
	global_load_dword v116, v181, s[36:37] sc1
	global_load_dword v117, v181, s[40:41] sc1
	global_load_dword v118, v181, s[48:49] sc1
	global_load_dword v119, v181, s[50:51] sc1
	s_waitcnt vmcnt(9)
	v_add_u32_e32 v120, v120, v110
	s_waitcnt vmcnt(8)
	v_add_u32_e32 v120, v120, v111
	s_waitcnt vmcnt(7)
	v_add_u32_e32 v120, v120, v112
	s_waitcnt vmcnt(6)
	v_add_u32_e32 v120, v120, v113
	s_waitcnt vmcnt(5)
	v_add_u32_e32 v120, v120, v114
	s_waitcnt vmcnt(4)
	v_add_u32_e32 v120, v120, v115
	s_waitcnt vmcnt(3)
	v_add_u32_e32 v120, v120, v116
	s_waitcnt vmcnt(2)
	v_add_u32_e32 v120, v120, v117
	s_waitcnt vmcnt(1)
	v_add_u32_e32 v120, v120, v118
	s_waitcnt vmcnt(0)
	v_add_u32_e32 v120, v120, v119
	v_cmp_eq_u32_e32 vcc, s76, v120
	s_cbranch_vccnz .LBB0_389
	s_and_b32 s46, s77, 0xff
	s_cmp_eq_u32 s46, 0
	s_mov_b64 s[46:47], -1
	s_sleep 6
	s_cbranch_scc0 .LBB0_394
	global_load_dword v120, v181, s[64:65] sc1
	s_waitcnt vmcnt(0)
	v_cmp_eq_u32_e32 vcc, 0, v120
	s_cbranch_vccnz .LBB0_396
	s_mov_b64 s[46:47], 0

; DI unsigned xb_ld(unsigned* p)              { return __hip_atomic_load(p, __ATOMIC_RELAXED, __HIP_MEMORY_SCOPE_AGENT); }
; DI unsigned xb_add(unsigned* p, unsigned v) { return __hip_atomic_fetch_add(p, v, __ATOMIC_RELAXED, __HIP_MEMORY_SCOPE_AGENT); }
; #define XB_SPIN(cond, bar) do { unsigned _sp = 0; while (cond) { __builtin_amdgcn_s_sleep(1); \
;     if ((++_sp & 255u) == 0u) { if (xb_ld(&(bar)[XB_TMO])) break; if (_sp > XB_SPIN_CAP) { atomicAdd(&(bar)[XB_TMO], 1u); break; } } } } while (0)
; DI void xcd_barrier(const XcdBarrier& b) {
;     ...
;             else XB_SPIN(xb_ld(&bar[XB_TOPGEN]) == tg, bar);
;             __builtin_amdgcn_fence(__ATOMIC_ACQUIRE, "agent");
;             xb_add(&bar[XB_XGEN(b.x)], 1u);
;             asm volatile("s_waitcnt vmcnt(0)" ::: "memory");
;         } else {
;             XB_SPIN(xb_ld(&bar[XB_XGEN(b.x)]) == gen, bar);
.LBB0_408:
	s_and_b32 s46, s75, 0xff
	s_mov_b64 s[82:83], -1
	s_cmp_lg_u32 s46, 0
	s_mov_b64 vcc, -1
	s_sleep 6
	s_cbranch_scc1 .LBB0_411
	global_load_dword v104, v181, s[64:65] sc1
	s_waitcnt vmcnt(0)
	v_cmp_eq_u32_e32 vcc, 0, v104
	s_cbranch_vccnz .LBB0_413
	s_mov_b64 vcc, 0
	s_mov_b64 s[46:47], -1

; DI unsigned xb_ld(unsigned* p)              { return __hip_atomic_load(p, __ATOMIC_RELAXED, __HIP_MEMORY_SCOPE_AGENT); }
; DI unsigned xb_add(unsigned* p, unsigned v) { return __hip_atomic_fetch_add(p, v, __ATOMIC_RELAXED, __HIP_MEMORY_SCOPE_AGENT); }
; #define XB_SPIN(cond, bar) do { unsigned _sp = 0; while (cond) { __builtin_amdgcn_s_sleep(1); \
;     if ((++_sp & 255u) == 0u) { if (xb_ld(&(bar)[XB_TMO])) break; if (_sp > XB_SPIN_CAP) { atomicAdd(&(bar)[XB_TMO], 1u); break; } } } } while (0)
; DI void xcd_barrier(const XcdBarrier& b) {
;     ...
;             else XB_SPIN(xb_ld(&bar[XB_TOPGEN]) == tg, bar);
;             __builtin_amdgcn_fence(__ATOMIC_ACQUIRE, "agent");
;             xb_add(&bar[XB_XGEN(b.x)], 1u);
;             asm volatile("s_waitcnt vmcnt(0)" ::: "memory");
;         } else {
;             XB_SPIN(xb_ld(&bar[XB_XGEN(b.x)]) == gen, bar);
.LBB0_425:
	s_and_b32 s46, s75, 0xff
	s_mov_b64 s[80:81], -1
	s_cmp_lg_u32 s46, 0
	s_mov_b64 s[82:83], -1
	s_sleep 6
	s_cbranch_scc1 .LBB0_428
	global_load_dword v104, v181, s[64:65] sc1
	s_waitcnt vmcnt(0)
	v_cmp_eq_u32_e32 vcc, 0, v104
	s_cbranch_vccnz .LBB0_430
	s_mov_b64 s[82:83], 0
	s_mov_b64 s[46:47], -1

; DI unsigned xb_ld(unsigned* p)              { return __hip_atomic_load(p, __ATOMIC_RELAXED, __HIP_MEMORY_SCOPE_AGENT); }
; DI unsigned xb_add(unsigned* p, unsigned v) { return __hip_atomic_fetch_add(p, v, __ATOMIC_RELAXED, __HIP_MEMORY_SCOPE_AGENT); }
; #define XB_SPIN(cond, bar) do { unsigned _sp = 0; while (cond) { __builtin_amdgcn_s_sleep(1); \
;     if ((++_sp & 255u) == 0u) { if (xb_ld(&(bar)[XB_TMO])) break; if (_sp > XB_SPIN_CAP) { atomicAdd(&(bar)[XB_TMO], 1u); break; } } } } while (0)
; DI void xcd_barrier(const XcdBarrier& b) {
;     ...
;             else XB_SPIN(xb_ld(&bar[XB_TOPGEN]) == tg, bar);
;             __builtin_amdgcn_fence(__ATOMIC_ACQUIRE, "agent");
;             xb_add(&bar[XB_XGEN(b.x)], 1u);
;             asm volatile("s_waitcnt vmcnt(0)" ::: "memory");
;         } else {
;             XB_SPIN(xb_ld(&bar[XB_XGEN(b.x)]) == gen, bar);
.LBB0_543:
	s_and_b32 s18, s47, 0xff
	s_mov_b64 s[16:17], -1
	s_cmp_lg_u32 s18, 0
	s_mov_b64 s[20:21], -1
	s_sleep 6
	s_cbranch_scc1 .LBB0_546
	global_load_dword v0, v181, s[64:65] sc1
	s_waitcnt vmcnt(0)
	v_cmp_eq_u32_e32 vcc, 0, v0
	s_cbranch_vccnz .LBB0_548
	s_mov_b64 s[20:21], 0
	s_mov_b64 s[18:19], -1

; DI unsigned xb_ld(unsigned* p)              { return __hip_atomic_load(p, __ATOMIC_RELAXED, __HIP_MEMORY_SCOPE_AGENT); }
; DI void xcd_barrier_complete(unsigned* bar, unsigned x, unsigned& nloc, unsigned& nx) {
;     const unsigned G = gridDim.x * gridDim.y * gridDim.z;
;     unsigned sum, cnt, mine, sp = 0u;
;     for (;;) {
;         sum = 0u; cnt = 0u; mine = 0u;
; #pragma unroll
;         for (unsigned j = 0; j < 16; ++j) { const unsigned c = xb_ld(&bar[XB_XCNT(j)]); sum += c; cnt += (c > 0u) ? 1u : 0u; mine = (j == x) ? c : mine; }
;         if (sum == G) break;
;         __builtin_amdgcn_s_sleep(1);
;         if ((++sp & 255u) == 0u) { if (xb_ld(&bar[XB_TMO])) break; if (sp > XB_SPIN_CAP) { atomicAdd(&bar[XB_TMO], 1u); break; } }
;     }
;     nloc = mine > 0u ? mine : 1u; nx = cnt > 0u ? cnt : 1u;
; }
.LBB0_695:
	v_readlane_b32 s4, v253, 54
	v_readlane_b32 s5, v253, 55
	s_waitcnt lgkmcnt(0)
	global_load_dword v0, v181, s[66:67] sc1
	s_mov_b64 s[6:7], -1
	s_nop 1
	global_load_dword v1, v181, s[4:5] sc1
	v_readlane_b32 s4, v253, 56
	v_readlane_b32 s5, v253, 57
	s_waitcnt vmcnt(0)
	v_add_u32_e32 v16, v1, v0
	s_nop 2
	global_load_dword v2, v181, s[4:5] sc1
	v_readlane_b32 s4, v253, 58
	v_readlane_b32 s5, v253, 59
	s_waitcnt vmcnt(0)
	v_add_u32_e32 v16, v16, v2
	s_nop 2
	global_load_dword v3, v181, s[4:5] sc1
	v_readlane_b32 s4, v253, 60
	v_readlane_b32 s5, v253, 61
	s_waitcnt vmcnt(0)
	v_add_u32_e32 v16, v16, v3
	s_nop 2
	global_load_dword v4, v181, s[4:5] sc1
	v_readlane_b32 s4, v253, 62
	v_readlane_b32 s5, v253, 63
	s_waitcnt vmcnt(0)
	v_add_u32_e32 v16, v16, v4
	s_nop 2
	global_load_dword v5, v181, s[4:5] sc1
	v_readlane_b32 s4, v254, 0
	v_readlane_b32 s5, v254, 1
	s_waitcnt vmcnt(0)
	v_add_u32_e32 v16, v16, v5
	s_nop 2
	global_load_dword v6, v181, s[4:5] sc1
	v_readlane_b32 s4, v254, 2
	v_readlane_b32 s5, v254, 3
	s_nop 4
	global_load_dword v7, v181, s[4:5] sc1
	global_load_dword v8, v181, s[22:23] sc1
	global_load_dword v9, v181, s[2:3] sc1
	global_load_dword v10, v181, s[34:35] sc1
	global_load_dword v11, v181, s[86:87] sc1
	global_load_dword v12, v181, s[36:37] sc1
	global_load_dword v13, v181, s[40:41] sc1
	global_load_dword v14, v181, s[48:49] sc1
	global_load_dword v15, v181, s[50:51] sc1
	s_mov_b64 s[4:5], -1
	s_waitcnt vmcnt(9)
	v_add_u32_e32 v16, v16, v6
	s_waitcnt vmcnt(8)
	v_add_u32_e32 v16, v16, v7
	s_waitcnt vmcnt(7)
	v_add_u32_e32 v16, v16, v8
	s_waitcnt vmcnt(6)
	v_add_u32_e32 v16, v16, v9
	s_waitcnt vmcnt(5)
	v_add_u32_e32 v16, v16, v10
	s_waitcnt vmcnt(4)
	v_add_u32_e32 v16, v16, v11
	s_waitcnt vmcnt(3)
	v_add_u32_e32 v16, v16, v12
	s_waitcnt vmcnt(2)
	v_add_u32_e32 v16, v16, v13
	s_waitcnt vmcnt(1)
	v_add_u32_e32 v16, v16, v14
	s_waitcnt vmcnt(0)
	v_add_u32_e32 v16, v16, v15
	v_cmp_eq_u32_e32 vcc, s20, v16
	s_cbranch_vccnz .LBB0_694
	s_and_b32 s4, s11, 0xff
	s_cmp_eq_u32 s4, 0
	s_mov_b64 s[4:5], -1
	s_mov_b64 s[8:9], -1
	s_sleep 6
	s_cbranch_scc0 .LBB0_699
	global_load_dword v16, v181, s[64:65] sc1
	s_waitcnt vmcnt(0)
	v_cmp_eq_u32_e32 vcc, 0, v16
	s_cbranch_vccnz .LBB0_701
	s_mov_b64 s[8:9], 0

; DI unsigned xb_ld(unsigned* p)              { return __hip_atomic_load(p, __ATOMIC_RELAXED, __HIP_MEMORY_SCOPE_AGENT); }
; DI void xcd_barrier_complete(unsigned* bar, unsigned x, unsigned& nloc, unsigned& nx) {
;     const unsigned G = gridDim.x * gridDim.y * gridDim.z;
;     unsigned sum, cnt, mine, sp = 0u;
;     for (;;) {
;         sum = 0u; cnt = 0u; mine = 0u;
; #pragma unroll
;         for (unsigned j = 0; j < 16; ++j) { const unsigned c = xb_ld(&bar[XB_XCNT(j)]); sum += c; cnt += (c > 0u) ? 1u : 0u; mine = (j == x) ? c : mine; }
;         if (sum == G) break;
;         __builtin_amdgcn_s_sleep(1);
;         if ((++sp & 255u) == 0u) { if (xb_ld(&bar[XB_TMO])) break; if (sp > XB_SPIN_CAP) { atomicAdd(&bar[XB_TMO], 1u); break; } }
;     }
;     nloc = mine > 0u ? mine : 1u; nx = cnt > 0u ? cnt : 1u;
; }
.LBB0_772:
	v_readlane_b32 s4, v253, 54
	v_readlane_b32 s5, v253, 55
	s_waitcnt lgkmcnt(0)
	global_load_dword v0, v181, s[66:67] sc1
	s_mov_b64 s[6:7], -1
	s_nop 1
	global_load_dword v1, v181, s[4:5] sc1
	v_readlane_b32 s4, v253, 56
	v_readlane_b32 s5, v253, 57
	s_waitcnt vmcnt(0)
	v_add_u32_e32 v16, v1, v0
	s_nop 2
	global_load_dword v2, v181, s[4:5] sc1
	v_readlane_b32 s4, v253, 58
	v_readlane_b32 s5, v253, 59
	s_waitcnt vmcnt(0)
	v_add_u32_e32 v16, v16, v2
	s_nop 2
	global_load_dword v3, v181, s[4:5] sc1
	v_readlane_b32 s4, v253, 60
	v_readlane_b32 s5, v253, 61
	s_waitcnt vmcnt(0)
	v_add_u32_e32 v16, v16, v3
	s_nop 2
	global_load_dword v4, v181, s[4:5] sc1
	v_readlane_b32 s4, v253, 62
	v_readlane_b32 s5, v253, 63
	s_waitcnt vmcnt(0)
	v_add_u32_e32 v16, v16, v4
	s_nop 2
	global_load_dword v5, v181, s[4:5] sc1
	v_readlane_b32 s4, v254, 0
	v_readlane_b32 s5, v254, 1
	s_waitcnt vmcnt(0)
	v_add_u32_e32 v16, v16, v5
	s_nop 2
	global_load_dword v6, v181, s[4:5] sc1
	v_readlane_b32 s4, v254, 2
	v_readlane_b32 s5, v254, 3
	s_nop 4
	global_load_dword v7, v181, s[4:5] sc1
	global_load_dword v8, v181, s[22:23] sc1
	global_load_dword v9, v181, s[2:3] sc1
	global_load_dword v10, v181, s[34:35] sc1
	global_load_dword v11, v181, s[86:87] sc1
	global_load_dword v12, v181, s[36:37] sc1
	global_load_dword v13, v181, s[40:41] sc1
	global_load_dword v14, v181, s[48:49] sc1
	global_load_dword v15, v181, s[50:51] sc1
	s_mov_b64 s[4:5], -1
	s_waitcnt vmcnt(9)
	v_add_u32_e32 v16, v16, v6
	s_waitcnt vmcnt(8)
	v_add_u32_e32 v16, v16, v7
	s_waitcnt vmcnt(7)
	v_add_u32_e32 v16, v16, v8
	s_waitcnt vmcnt(6)
	v_add_u32_e32 v16, v16, v9
	s_waitcnt vmcnt(5)
	v_add_u32_e32 v16, v16, v10
	s_waitcnt vmcnt(4)
	v_add_u32_e32 v16, v16, v11
	s_waitcnt vmcnt(3)
	v_add_u32_e32 v16, v16, v12
	s_waitcnt vmcnt(2)
	v_add_u32_e32 v16, v16, v13
	s_waitcnt vmcnt(1)
	v_add_u32_e32 v16, v16, v14
	s_waitcnt vmcnt(0)
	v_add_u32_e32 v16, v16, v15
	v_cmp_eq_u32_e32 vcc, s20, v16
	s_cbranch_vccnz .LBB0_771
	s_and_b32 s4, s13, 0xff
	s_cmp_eq_u32 s4, 0
	s_mov_b64 s[4:5], -1
	s_mov_b64 s[8:9], -1
	s_sleep 6
	s_cbranch_scc0 .LBB0_776
	global_load_dword v16, v181, s[64:65] sc1
	s_waitcnt vmcnt(0)
	v_cmp_eq_u32_e32 vcc, 0, v16
	s_cbranch_vccnz .LBB0_778
	s_mov_b64 s[8:9], 0

; DI unsigned xb_ld(unsigned* p)              { return __hip_atomic_load(p, __ATOMIC_RELAXED, __HIP_MEMORY_SCOPE_AGENT); }
; DI unsigned xb_add(unsigned* p, unsigned v) { return __hip_atomic_fetch_add(p, v, __ATOMIC_RELAXED, __HIP_MEMORY_SCOPE_AGENT); }
; #define XB_SPIN(cond, bar) do { unsigned _sp = 0; while (cond) { __builtin_amdgcn_s_sleep(1); \
;     if ((++_sp & 255u) == 0u) { if (xb_ld(&(bar)[XB_TMO])) break; if (_sp > XB_SPIN_CAP) { atomicAdd(&(bar)[XB_TMO], 1u); break; } } } } while (0)
; DI void xcd_barrier(const XcdBarrier& b) {
;     ...
;             else XB_SPIN(xb_ld(&bar[XB_TOPGEN]) == tg, bar);
;             __builtin_amdgcn_fence(__ATOMIC_ACQUIRE, "agent");
;             xb_add(&bar[XB_XGEN(b.x)], 1u);
;             asm volatile("s_waitcnt vmcnt(0)" ::: "memory");
;         } else {
;             XB_SPIN(xb_ld(&bar[XB_XGEN(b.x)]) == gen, bar);
.LBB0_790:
	s_and_b32 s20, s69, 0xff
	s_mov_b64 s[18:19], -1
	s_cmp_lg_u32 s20, 0
	s_mov_b64 s[46:47], -1
	s_sleep 6
	s_cbranch_scc1 .LBB0_793
	global_load_dword v0, v181, s[64:65] sc1
	s_waitcnt vmcnt(0)
	v_cmp_eq_u32_e32 vcc, 0, v0
	s_cbranch_vccnz .LBB0_795
	s_mov_b64 s[46:47], 0
	s_mov_b64 s[20:21], -1

; DI unsigned xb_ld(unsigned* p)              { return __hip_atomic_load(p, __ATOMIC_RELAXED, __HIP_MEMORY_SCOPE_AGENT); }
; DI void xcd_barrier_complete(unsigned* bar, unsigned x, unsigned& nloc, unsigned& nx) {
;     const unsigned G = gridDim.x * gridDim.y * gridDim.z;
;     unsigned sum, cnt, mine, sp = 0u;
;     for (;;) {
;         sum = 0u; cnt = 0u; mine = 0u;
; #pragma unroll
;         for (unsigned j = 0; j < 16; ++j) { const unsigned c = xb_ld(&bar[XB_XCNT(j)]); sum += c; cnt += (c > 0u) ? 1u : 0u; mine = (j == x) ? c : mine; }
;         if (sum == G) break;
;         __builtin_amdgcn_s_sleep(1);
;         if ((++sp & 255u) == 0u) { if (xb_ld(&bar[XB_TMO])) break; if (sp > XB_SPIN_CAP) { atomicAdd(&bar[XB_TMO], 1u); break; } }
;     }
;     nloc = mine > 0u ? mine : 1u; nx = cnt > 0u ? cnt : 1u;
; }
.LBB0_921:
	v_readlane_b32 s4, v253, 54
	v_readlane_b32 s5, v253, 55
	s_waitcnt lgkmcnt(0)
	global_load_dword v0, v181, s[66:67] sc1
	s_mov_b64 s[6:7], -1
	s_nop 1
	global_load_dword v1, v181, s[4:5] sc1
	v_readlane_b32 s4, v253, 56
	v_readlane_b32 s5, v253, 57
	s_waitcnt vmcnt(0)
	v_add_u32_e32 v16, v1, v0
	s_nop 2
	global_load_dword v2, v181, s[4:5] sc1
	v_readlane_b32 s4, v253, 58
	v_readlane_b32 s5, v253, 59
	s_waitcnt vmcnt(0)
	v_add_u32_e32 v16, v16, v2
	s_nop 2
	global_load_dword v3, v181, s[4:5] sc1
	v_readlane_b32 s4, v253, 60
	v_readlane_b32 s5, v253, 61
	s_waitcnt vmcnt(0)
	v_add_u32_e32 v16, v16, v3
	s_nop 2
	global_load_dword v4, v181, s[4:5] sc1
	v_readlane_b32 s4, v253, 62
	v_readlane_b32 s5, v253, 63
	s_waitcnt vmcnt(0)
	v_add_u32_e32 v16, v16, v4
	s_nop 2
	global_load_dword v5, v181, s[4:5] sc1
	v_readlane_b32 s4, v254, 0
	v_readlane_b32 s5, v254, 1
	s_waitcnt vmcnt(0)
	v_add_u32_e32 v16, v16, v5
	s_nop 2
	global_load_dword v6, v181, s[4:5] sc1
	v_readlane_b32 s4, v254, 2
	v_readlane_b32 s5, v254, 3
	s_nop 4
	global_load_dword v7, v181, s[4:5] sc1
	global_load_dword v8, v181, s[22:23] sc1
	global_load_dword v9, v181, s[2:3] sc1
	global_load_dword v10, v181, s[34:35] sc1
	global_load_dword v11, v181, s[86:87] sc1
	global_load_dword v12, v181, s[36:37] sc1
	global_load_dword v13, v181, s[40:41] sc1
	global_load_dword v14, v181, s[48:49] sc1
	global_load_dword v15, v181, s[50:51] sc1
	s_mov_b64 s[4:5], -1
	s_waitcnt vmcnt(9)
	v_add_u32_e32 v16, v16, v6
	s_waitcnt vmcnt(8)
	v_add_u32_e32 v16, v16, v7
	s_waitcnt vmcnt(7)
	v_add_u32_e32 v16, v16, v8
	s_waitcnt vmcnt(6)
	v_add_u32_e32 v16, v16, v9
	s_waitcnt vmcnt(5)
	v_add_u32_e32 v16, v16, v10
	s_waitcnt vmcnt(4)
	v_add_u32_e32 v16, v16, v11
	s_waitcnt vmcnt(3)
	v_add_u32_e32 v16, v16, v12
	s_waitcnt vmcnt(2)
	v_add_u32_e32 v16, v16, v13
	s_waitcnt vmcnt(1)
	v_add_u32_e32 v16, v16, v14
	s_waitcnt vmcnt(0)
	v_add_u32_e32 v16, v16, v15
	v_cmp_eq_u32_e32 vcc, s12, v16
	s_cbranch_vccnz .LBB0_920
	s_and_b32 s4, s11, 0xff
	s_cmp_eq_u32 s4, 0
	s_mov_b64 s[4:5], -1
	s_mov_b64 s[8:9], -1
	s_sleep 6
	s_cbranch_scc0 .LBB0_925
	global_load_dword v16, v181, s[64:65] sc1
	s_waitcnt vmcnt(0)
	v_cmp_eq_u32_e32 vcc, 0, v16
	s_cbranch_vccnz .LBB0_927
	s_mov_b64 s[8:9], 0
